# attention loop: vmcnt(0) moved from before first V ds_read to its real consumers (V ds_write + end barrier)
# speedup vs baseline: 1.0540x; 1.0007x over previous
; #define SB_ __builtin_amdgcn_sched_barrier(0)
; DI void attn_item64(const Params& p, int it, char* smem) {
;     ...
;   for (int kt = 0; kt < NKT; ++kt) {
;     const char* cur = smem + (kt & 1) * STAGE;
;     const bool more = kt + 1 < NKT;
;     if (more) {
;       const bf16_t* kn = Kb + (size_t)(kt + 1) * 64 * QKD; const bf16_t* vn = Vb + (kt + 1) * 64;
;       char* nx = smem + ((kt + 1) & 1) * STAGE;
;       GLDS(kn + kgo0, nx + klo0); if (k1v) GLDS(kn + kgo1, nx + klo1);
;       rv0 = *(const uint4*)(vn + vgo0);
;     }
;     SB_;
; #pragma unroll
;     for (int t2 = 0; t2 < 2; ++t2) {
;       const char* kpe = cur + (t2 * 32 + r) * KROW + swo;
;       const char* kpo = kpe - 2 * sb32;
;       f32x16 sa, sb;
;       { const bf16x8 kf = *(const bf16x8*)(kpe); sa = MFMA(kf, qfa[0], sinit); sb = MFMA(kf, qfb[0], sinit); }
; #pragma unroll
;       for (int c = 1; c < 6; ++c) { const bf16x8 kf = *(const bf16x8*)(((c & 1) ? kpo : kpe) + c * 32); sa = MFMA(kf, qfa[c], sa); sb = MFMA(kf, qfb[c], sb); }
;       SB_;
;       float lsa = 0.f, lsb = 0.f;
; #pragma unroll
;       for (int i = 0; i < 16; ++i) { const float e = __builtin_amdgcn_exp2f(sa[i]); sa[i] = e; lsa += e; const float f = __builtin_amdgcn_exp2f(sb[i]); sb[i] = f; lsb += f; }
;       la += lsa; lb += lsb;
;       SB_;
; #pragma unroll
;       for (int s2 = 0; s2 < 2; ++s2) {
;         uint4 pu, pv;
;         pu.x = pk_bf16(sa[8 * s2 + 0], sa[8 * s2 + 1]); pu.y = pk_bf16(sa[8 * s2 + 2], sa[8 * s2 + 3]); pu.z = pk_bf16(sa[8 * s2 + 4], sa[8 * s2 + 5]); pu.w = pk_bf16(sa[8 * s2 + 6], sa[8 * s2 + 7]);
;         pv.x = pk_bf16(sb[8 * s2 + 0], sb[8 * s2 + 1]); pv.y = pk_bf16(sb[8 * s2 + 2], sb[8 * s2 + 3]); pv.z = pk_bf16(sb[8 * s2 + 4], sb[8 * s2 + 5]); pv.w = pk_bf16(sb[8 * s2 + 6], sb[8 * s2 + 7]);
;         const bf16x8 pa_ = __builtin_bit_cast(bf16x8, pu), pb_ = __builtin_bit_cast(bf16x8, pv);
; #pragma unroll
;         for (int vt = 0; vt < 2; ++vt) {
;           const char* vp = cur + KBYTES + (vt * 32 + r) * VROW + (t2 * 32 + 16 * s2 + 4 * hh) * 2;
;           const uint2 lo = *(const uint2*)(vp), hi = *(const uint2*)(vp + 16);
;           uint4 vu; vu.x = lo.x; vu.y = lo.y; vu.z = hi.x; vu.w = hi.y;
;           const bf16x8 vf = __builtin_bit_cast(bf16x8, vu);
;           oa[vt] = MFMA(vf, pa_, oa[vt]);
;           ob[vt] = MFMA(vf, pb_, ob[vt]);
;         }
;       }
.LBB0_548:
	s_or_b64 exec, exec, s[4:5]
	global_load_dwordx4 v[160:163], v[170:171], off
	s_cmp_eq_u32 s7, 1
	s_cselect_b32 s4, 0, 0x5200
	v_or_b32_e32 v80, s4, v211
	v_add_u32_e32 v80, v80, v210
	v_or_b32_e32 v81, s4, v164
	v_add_u32_e32 v168, v80, v212
	v_add3_u32 v213, v80, v207, v206
	v_add_u32_e32 v80, s6, v209
	v_add_u32_e32 v188, v168, v206
	v_add_u32_e32 v195, v81, v208
	v_add_u32_e32 v238, 0x3000, v80
	ds_read_b128 v[176:179], v168
	ds_read_b128 v[180:183], v168 offset:64
	s_waitcnt lgkmcnt(0)
	v_mfma_f32_32x32x16_bf16 v[80:95], v[176:179], v[152:155], v[64:79]
	v_mfma_f32_32x32x16_bf16 v[96:111], v[176:179], v[156:159], v[64:79]
	ds_read_b128 v[176:179], v188 offset:32
	ds_read_b128 v[184:187], v168 offset:128
	s_waitcnt lgkmcnt(0)
	v_mfma_f32_32x32x16_bf16 v[80:95], v[176:179], v[136:139], v[80:95]
	v_mfma_f32_32x32x16_bf16 v[96:111], v[176:179], v[140:143], v[96:111]
	v_mfma_f32_32x32x16_bf16 v[80:95], v[180:183], v[144:147], v[80:95]
	v_mfma_f32_32x32x16_bf16 v[96:111], v[180:183], v[148:151], v[96:111]
	ds_read_b128 v[176:179], v188 offset:96
	ds_read_b128 v[180:183], v188 offset:160
	s_waitcnt lgkmcnt(0)
	v_mfma_f32_32x32x16_bf16 v[80:95], v[176:179], v[112:115], v[80:95]
	v_mfma_f32_32x32x16_bf16 v[96:111], v[176:179], v[124:127], v[96:111]
	v_mfma_f32_32x32x16_bf16 v[80:95], v[184:187], v[128:131], v[80:95]
	v_mfma_f32_32x32x16_bf16 v[96:111], v[184:187], v[132:135], v[96:111]
	v_mfma_f32_32x32x16_bf16 v[80:95], v[180:183], v[116:119], v[80:95]
	v_mfma_f32_32x32x16_bf16 v[96:111], v[180:183], v[120:123], v[96:111]
	s_nop 10
	v_exp_f32_e32 v214, v80
	v_exp_f32_e32 v215, v81
	v_exp_f32_e32 v216, v82
	v_exp_f32_e32 v217, v83
	v_add_f32_e32 v80, 0, v214
	v_exp_f32_e32 v218, v84
	v_add_f32_e32 v80, v215, v80
	v_exp_f32_e32 v219, v85
	v_add_f32_e32 v80, v216, v80
	v_exp_f32_e32 v222, v86
	v_add_f32_e32 v80, v217, v80
	v_add_f32_e32 v80, v218, v80
	v_add_f32_e32 v80, v219, v80
	v_exp_f32_e32 v96, v96
	v_exp_f32_e32 v97, v97
	v_exp_f32_e32 v98, v98
	v_exp_f32_e32 v99, v99
	v_exp_f32_e32 v100, v100
	v_exp_f32_e32 v101, v101
	v_exp_f32_e32 v102, v102
	v_exp_f32_e32 v188, v87
	v_exp_f32_e32 v189, v103
	v_exp_f32_e32 v186, v88
	v_exp_f32_e32 v187, v104
	v_exp_f32_e32 v190, v89
	v_exp_f32_e32 v191, v105
	v_exp_f32_e32 v192, v90
	v_exp_f32_e32 v193, v106
	v_exp_f32_e32 v180, v91
	v_exp_f32_e32 v181, v107
	v_exp_f32_e32 v182, v92
	v_exp_f32_e32 v183, v108
	v_exp_f32_e32 v184, v93
	v_exp_f32_e32 v185, v109
	v_exp_f32_e32 v176, v94
	v_exp_f32_e32 v177, v110
	v_exp_f32_e32 v178, v95
	v_exp_f32_e32 v179, v111
	v_add_f32_e32 v194, v222, v80
	v_add_u32_e32 v239, 0x3000, v195
	ds_read2_b64 v[80:83], v239 offset1:2
	v_cvt_pk_bf16_f32 v84, v214, v215
	v_cvt_pk_bf16_f32 v85, v216, v217
	v_cvt_pk_bf16_f32 v86, v218, v219
	v_cvt_pk_bf16_f32 v87, v222, v188
	v_cvt_pk_bf16_f32 v88, v96, v97
	v_cvt_pk_bf16_f32 v89, v98, v99
	v_cvt_pk_bf16_f32 v90, v100, v101
	v_cvt_pk_bf16_f32 v91, v102, v189
	v_add_u32_e32 v240, 0x4000, v195
	s_waitcnt lgkmcnt(0)
	v_mfma_f32_32x32x16_bf16 v[48:63], v[80:83], v[84:87], v[48:63]
	v_mfma_f32_32x32x16_bf16 v[32:47], v[80:83], v[88:91], v[32:47]
	ds_read2_b64 v[80:83], v240 offset0:32 offset1:34
	ds_read2_b64 v[214:217], v239 offset0:4 offset1:6
	ds_read2_b64 v[222:225], v240 offset0:36 offset1:38
	s_waitcnt lgkmcnt(2)
	v_mfma_f32_32x32x16_bf16 v[16:31], v[80:83], v[84:87], v[16:31]
	v_add_f32_e32 v84, 0, v96
	v_add_f32_e32 v84, v97, v84
	v_add_f32_e32 v84, v98, v84
	v_add_f32_e32 v84, v99, v84
	v_add_f32_e32 v84, v100, v84
	v_add_f32_e32 v84, v101, v84
	v_add_f32_e32 v195, v102, v84
	v_mfma_f32_32x32x16_bf16 v[0:15], v[80:83], v[88:91], v[0:15]
	ds_read_b128 v[226:229], v168 offset:6144
	ds_read_b128 v[230:233], v168 offset:6208
	s_waitcnt lgkmcnt(1)
	v_mfma_f32_32x32x16_bf16 v[80:95], v[226:229], v[152:155], v[64:79]
	v_mfma_f32_32x32x16_bf16 v[96:111], v[226:229], v[156:159], v[64:79]
	ds_read_b128 v[226:229], v213 offset:32
	ds_read_b128 v[234:237], v168 offset:6272
	s_waitcnt lgkmcnt(1)
	v_mfma_f32_32x32x16_bf16 v[80:95], v[226:229], v[136:139], v[80:95]
	v_mfma_f32_32x32x16_bf16 v[96:111], v[226:229], v[140:143], v[96:111]
	v_mfma_f32_32x32x16_bf16 v[80:95], v[230:233], v[144:147], v[80:95]
	v_mfma_f32_32x32x16_bf16 v[96:111], v[230:233], v[148:151], v[96:111]
	ds_read_b128 v[226:229], v213 offset:96
	ds_read_b128 v[230:233], v213 offset:160
	s_waitcnt lgkmcnt(1)
	v_mfma_f32_32x32x16_bf16 v[80:95], v[226:229], v[112:115], v[80:95]
	v_mfma_f32_32x32x16_bf16 v[96:111], v[226:229], v[124:127], v[96:111]
	v_mfma_f32_32x32x16_bf16 v[80:95], v[234:237], v[128:131], v[80:95]
	v_mfma_f32_32x32x16_bf16 v[96:111], v[234:237], v[132:135], v[96:111]
	s_waitcnt lgkmcnt(0)
; #define MFMA(a, b, c) __builtin_amdgcn_mfma_f32_32x32x16_bf16((a), (b), (c), 0, 0, 0)
; DI unsigned pk_bf16(float lo, float hi) { f32x2v v = {lo, hi}; bf16x2v b = __builtin_convertvector(v, bf16x2v); return __builtin_bit_cast(unsigned, b); }
; #define SB_ __builtin_amdgcn_sched_barrier(0)
; #define ATT64_STORE(base) do { \
;     { uint2* d = (uint2*)((base) + vlo0); d[0] = make_uint2(rv0.x, rv0.y); d[1] = make_uint2(rv0.z, rv0.w); } } while (0)
; DI void attn_item64(const Params& p, int it, char* smem) {
;     ...
;       for (int c = 1; c < 6; ++c) { const bf16x8 kf = *(const bf16x8*)(((c & 1) ? kpo : kpe) + c * 32); sa = MFMA(kf, qfa[c], sa); sb = MFMA(kf, qfb[c], sb); }
;       SB_;
;       float lsa = 0.f, lsb = 0.f;
; #pragma unroll
;       for (int i = 0; i < 16; ++i) { const float e = __builtin_amdgcn_exp2f(sa[i]); sa[i] = e; lsa += e; const float f = __builtin_amdgcn_exp2f(sb[i]); sb[i] = f; lsb += f; }
;       la += lsa; lb += lsb;
;       SB_;
; #pragma unroll
;       for (int s2 = 0; s2 < 2; ++s2) {
;         uint4 pu, pv;
;         pu.x = pk_bf16(sa[8 * s2 + 0], sa[8 * s2 + 1]); pu.y = pk_bf16(sa[8 * s2 + 2], sa[8 * s2 + 3]); pu.z = pk_bf16(sa[8 * s2 + 4], sa[8 * s2 + 5]); pu.w = pk_bf16(sa[8 * s2 + 6], sa[8 * s2 + 7]);
;         pv.x = pk_bf16(sb[8 * s2 + 0], sb[8 * s2 + 1]); pv.y = pk_bf16(sb[8 * s2 + 2], sb[8 * s2 + 3]); pv.z = pk_bf16(sb[8 * s2 + 4], sb[8 * s2 + 5]); pv.w = pk_bf16(sb[8 * s2 + 6], sb[8 * s2 + 7]);
;         const bf16x8 pa_ = __builtin_bit_cast(bf16x8, pu), pb_ = __builtin_bit_cast(bf16x8, pv);
; #pragma unroll
;         for (int vt = 0; vt < 2; ++vt) {
;           const char* vp = cur + KBYTES + (vt * 32 + r) * VROW + (t2 * 32 + 16 * s2 + 4 * hh) * 2;
;           const uint2 lo = *(const uint2*)(vp), hi = *(const uint2*)(vp + 16);
;           uint4 vu; vu.x = lo.x; vu.y = lo.y; vu.z = hi.x; vu.w = hi.y;
;           const bf16x8 vf = __builtin_bit_cast(bf16x8, vu);
;           oa[vt] = MFMA(vf, pa_, oa[vt]);
;           ob[vt] = MFMA(vf, pb_, ob[vt]);
;         }
;       }
;       SB_;
;     }
;     SB_;
;     if (more) { char* nxt = smem + ((kt + 1) & 1) * STAGE; ATT64_STORE(nxt); }
;     __syncthreads();
	v_mfma_f32_32x32x16_bf16 v[80:95], v[230:233], v[116:119], v[80:95]
	v_mfma_f32_32x32x16_bf16 v[96:111], v[230:233], v[120:123], v[96:111]
	s_nop 10
	v_exp_f32_e32 v168, v80
	v_exp_f32_e32 v213, v81
	v_exp_f32_e32 v233, v96
	v_exp_f32_e32 v96, v82
	v_exp_f32_e32 v234, v97
	v_exp_f32_e32 v97, v83
	v_add_f32_e32 v80, 0, v168
	v_exp_f32_e32 v235, v98
	v_exp_f32_e32 v98, v84
	v_add_f32_e32 v80, v213, v80
	v_exp_f32_e32 v236, v99
	v_exp_f32_e32 v99, v85
	v_add_f32_e32 v80, v96, v80
	v_add_f32_e32 v80, v97, v80
	v_add_f32_e32 v80, v98, v80
	v_exp_f32_e32 v237, v100
	v_exp_f32_e32 v241, v101
	v_exp_f32_e32 v100, v86
	v_exp_f32_e32 v101, v102
	v_exp_f32_e32 v102, v87
	v_exp_f32_e32 v103, v103
	v_exp_f32_e32 v218, v88
	v_exp_f32_e32 v219, v104
	v_exp_f32_e32 v104, v89
	v_exp_f32_e32 v105, v105
	v_exp_f32_e32 v226, v90
	v_exp_f32_e32 v227, v106
	v_exp_f32_e32 v106, v91
	v_exp_f32_e32 v107, v107
	v_exp_f32_e32 v228, v92
	v_exp_f32_e32 v229, v108
	v_exp_f32_e32 v108, v93
	v_exp_f32_e32 v109, v109
	v_exp_f32_e32 v230, v94
	v_exp_f32_e32 v231, v110
	v_exp_f32_e32 v110, v95
	v_exp_f32_e32 v111, v111
	v_add_f32_e32 v232, v99, v80
	v_cvt_pk_bf16_f32 v80, v186, v190
	v_cvt_pk_bf16_f32 v81, v192, v180
	v_cvt_pk_bf16_f32 v82, v182, v184
	v_cvt_pk_bf16_f32 v83, v176, v178
	v_cvt_pk_bf16_f32 v84, v187, v191
	v_cvt_pk_bf16_f32 v85, v193, v181
	v_mfma_f32_32x32x16_bf16 v[48:63], v[214:217], v[80:83], v[48:63]
	v_cvt_pk_bf16_f32 v86, v183, v185
	v_cvt_pk_bf16_f32 v87, v177, v179
	v_cvt_pk_bf16_f32 v88, v233, v234
	v_cvt_pk_bf16_f32 v89, v235, v236
	v_cvt_pk_bf16_f32 v90, v237, v241
	v_cvt_pk_bf16_f32 v91, v101, v103
	v_mfma_f32_32x32x16_bf16 v[16:31], v[222:225], v[80:83], v[16:31]
	ds_read2_b64 v[80:83], v239 offset0:8 offset1:10
	v_mfma_f32_32x32x16_bf16 v[32:47], v[214:217], v[84:87], v[32:47]
	v_mfma_f32_32x32x16_bf16 v[0:15], v[222:225], v[84:87], v[0:15]
	v_cvt_pk_bf16_f32 v84, v168, v213
	v_cvt_pk_bf16_f32 v85, v96, v97
	v_cvt_pk_bf16_f32 v86, v98, v99
	v_cvt_pk_bf16_f32 v87, v100, v102
	s_waitcnt lgkmcnt(0)
	s_nop 0
	v_mfma_f32_32x32x16_bf16 v[48:63], v[80:83], v[84:87], v[48:63]
	v_mfma_f32_32x32x16_bf16 v[32:47], v[80:83], v[88:91], v[32:47]
	ds_read2_b64 v[80:83], v240 offset0:40 offset1:42
	ds_read2_b64 v[92:95], v239 offset0:12 offset1:14
	ds_read2_b64 v[96:99], v240 offset0:44 offset1:46
	s_waitcnt lgkmcnt(2)
	v_mfma_f32_32x32x16_bf16 v[16:31], v[80:83], v[84:87], v[16:31]
	v_add_f32_e32 v84, 0, v233
	v_add_f32_e32 v84, v234, v84
	v_add_f32_e32 v84, v235, v84
	v_add_f32_e32 v84, v236, v84
	v_add_f32_e32 v84, v237, v84
	v_add_f32_e32 v233, v241, v84
	v_pk_add_f32 v[84:85], v[188:189], v[194:195]
	v_mfma_f32_32x32x16_bf16 v[0:15], v[80:83], v[88:91], v[0:15]
	v_add_f32_e64 v80, v186, v84
	v_add_f32_e64 v81, v187, v85
	v_add_f32_e64 v90, v100, v232
	v_add_f32_e64 v91, v101, v233
	v_add_f32_e64 v80, v190, v80
	v_add_f32_e64 v81, v191, v81
	v_pk_add_f32 v[90:91], v[102:103], v[90:91]
	v_pk_add_f32 v[84:85], v[192:193], v[80:81]
	v_cvt_pk_bf16_f32 v80, v218, v104
	v_pk_add_f32 v[84:85], v[180:181], v[84:85]
	v_cvt_pk_bf16_f32 v81, v226, v106
	v_pk_add_f32 v[84:85], v[182:183], v[84:85]
	v_cvt_pk_bf16_f32 v82, v228, v108
	v_cvt_pk_bf16_f32 v83, v230, v110
	v_pk_add_f32 v[88:89], v[184:185], v[84:85]
	v_cvt_pk_bf16_f32 v84, v219, v105
	v_cvt_pk_bf16_f32 v85, v227, v107
	v_cvt_pk_bf16_f32 v86, v229, v109
	v_cvt_pk_bf16_f32 v87, v231, v111
	v_pk_add_f32 v[90:91], v[218:219], v[90:91]
	s_waitcnt lgkmcnt(1)
	v_mfma_f32_32x32x16_bf16 v[48:63], v[92:95], v[80:83], v[48:63]
	v_add_f32_e64 v90, v104, v90
	v_add_f32_e64 v91, v105, v91
	v_add_f32_e64 v88, v176, v88
	v_add_f32_e64 v89, v177, v89
	v_add_f32_e64 v88, v178, v88
	v_add_f32_e64 v89, v179, v89
	v_pk_add_f32 v[88:89], v[166:167], v[88:89]
	v_mfma_f32_32x32x16_bf16 v[32:47], v[92:95], v[84:87], v[32:47]
	s_waitcnt lgkmcnt(0)
	v_mfma_f32_32x32x16_bf16 v[16:31], v[96:99], v[80:83], v[16:31]
	v_add_f32_e64 v80, v226, v90
	v_add_f32_e64 v81, v227, v91
	v_add_f32_e64 v80, v106, v80
	v_add_f32_e64 v81, v107, v81
	v_add_f32_e64 v80, v228, v80
	v_add_f32_e64 v81, v229, v81
	v_pk_add_f32 v[80:81], v[108:109], v[80:81]
	v_mfma_f32_32x32x16_bf16 v[0:15], v[96:99], v[84:87], v[0:15]
	v_add_f32_e64 v80, v230, v80
	v_add_f32_e64 v81, v231, v81
	v_add_f32_e64 v80, v110, v80
	v_add_f32_e64 v81, v111, v81
	v_add_f32_e64 v166, v88, v80
	v_add_f32_e64 v167, v89, v81
	s_add_i32 s8, s8, 1
	v_lshl_add_u64 v[170:171], v[170:171], 0, s[30:31]
	v_lshl_add_u64 v[172:173], v[172:173], 0, s[34:35]
	s_cmp_lg_u32 s8, 36
	v_lshl_add_u64 v[174:175], v[174:175], 0, s[34:35]
	s_waitcnt vmcnt(0)
	ds_write2_b64 v238, v[160:161], v[162:163] offset1:1
	s_waitcnt lgkmcnt(0)
	s_barrier
	s_cbranch_scc0 .LBB0_551
